# in-projection conv/gate epilogue: 8-byte row-per-lane stores paired through v_permlane16_swap into 16-byte stores (16 dwordx2 -> 8 dwordx4 per wave)
# speedup vs baseline: 1.0043x; 1.0021x over previous
; __device__ __forceinline__ unsigned cvt_pk_bf16(float lo, float hi) { unsigned r; asm volatile("v_cvt_pk_bf16_f32 %0, %1, %2" : "=v"(r) : "v"(lo), "v"(hi)); return r; }
; __device__ __forceinline__ float dpp_ror1(float x)  { return __builtin_bit_cast(float, __builtin_amdgcn_update_dpp(0, __builtin_bit_cast(int, x), 0x121, 0xF, 0xF, false)); }
; __device__ __forceinline__ float dpp_ror15(float x) { return __builtin_bit_cast(float, __builtin_amdgcn_update_dpp(0, __builtin_bit_cast(int, x), 0x12F, 0xF, 0xF, false)); }
;     __host__ __device__ bool next(int i, Unit& u) const { const long L = (long)i * G + c; if (L >= nwg) return false; u.pm = 0; u.pn = c % nN; return true; }
;     __device__ __forceinline__ void operator()(const f32x4 (&acc)[2][2][4][2], const Unit& u, int wr, int wc, int fr, int fq) const {
;     ...
;             const int ch0 = 64 * (u.pn - 12) + 16 * wc + 4 * fq;
;             const f32x4 w0 = *(const f32x4*)(convw + ch0), w1 = *(const f32x4*)(convw + nconv + ch0), w2 = *(const f32x4*)(convw + 2 * nconv + ch0);
; #pragma unroll
;             for (int ai = 0; ai < 2; ++ai) {
;                 f32x4 cv[4], rr[4], ll[4];
; #pragma unroll
;                 for (int m = 0; m < 4; ++m) { cv[m] = acc[ai][0][m][0] * acc[ai][0][m][1];
; #pragma unroll
;                     for (int e = 0; e < 4; ++e) { rr[m][e] = dpp_ror1(cv[m][e]); ll[m][e] = dpp_ror15(cv[m][e]); } }
; #pragma unroll
;                 for (int m = 0; m < 4; ++m) {
;                     const f32x4 z = (f32x4){0.f, 0.f, 0.f, 0.f};
;                     const f32x4 prev = fr > 0 ? rr[m] : (m > 0 ? rr[m > 0 ? m - 1 : 0] : z), next = fr < 15 ? ll[m] : (m < 3 ? ll[m < 3 ? m + 1 : 3] : z);
;                     const f32x4 o = acc[ai][1][m][0] * (w0 * prev + w1 * cv[m] + w2 * next);
;                     const f32x4 gq = acc[ai][1][m][1]; f32x4 gs;
; #pragma unroll
;                     for (int e = 0; e < 4; ++e) gs[e] = gq[e] * __builtin_amdgcn_rcpf(1.f + __expf(-gq[e]));
;                     const size_t r = (size_t)(row0 + ai * HALF + m * 16);
;                     *(u32x2*)(CATc + r * ldcat + ch0) = (u32x2){cvt_pk_bf16(o[0], o[1]), cvt_pk_bf16(o[2], o[3])};
;                     *(u32x2*)(GS + r * ldg + ch0) = (u32x2){cvt_pk_bf16(gs[0], gs[1]), cvt_pk_bf16(gs[2], gs[3])};
.LBB0_261:
	v_lshl_add_u32 v172, s52, 6, v223
	v_lshlrev_b64 v[130:131], 2, v[172:173]
	v_lshl_add_u64 v[132:133], s[62:63], 0, v[130:131]
	v_lshl_add_u64 v[134:135], s[72:73], 0, v[130:131]
	global_load_dwordx4 v[138:141], v[132:133], off
	s_nop 0
	global_load_dwordx4 v[134:137], v[134:135], off
	v_lshl_add_u64 v[130:131], s[74:75], 0, v[130:131]
	global_load_dwordx4 v[130:133], v[130:131], off
	v_pk_mul_f32 v[142:143], v[128:129], v[124:125]
	v_mov_b32_e32 v201, v173
	v_mov_b32_e32 v212, v173
	v_mov_b32_e32 v203, v173
	v_mov_b32_dpp v201, v142 row_ror:1 row_mask:0xf bank_mask:0xf
	v_mov_b32_dpp v212, v143 row_ror:1 row_mask:0xf bank_mask:0xf
	v_cndmask_b32_e64 v159, v212, 0, s[4:5]
	v_cndmask_b32_e64 v158, v201, 0, s[4:5]
	v_mov_b32_e32 v204, v173
	v_pk_mul_f32 v[148:149], v[126:127], v[122:123]
	v_mov_b32_e32 v195, v173
	v_mov_b32_e32 v197, v173
	v_mov_b32_dpp v203, v142 row_ror:15 row_mask:0xf bank_mask:0xf
	v_mov_b32_dpp v204, v143 row_ror:15 row_mask:0xf bank_mask:0xf
	v_mov_b32_dpp v195, v148 row_ror:1 row_mask:0xf bank_mask:0xf
	v_mov_b32_dpp v197, v149 row_ror:1 row_mask:0xf bank_mask:0xf
	v_cndmask_b32_e64 v161, v197, 0, s[4:5]
	v_cndmask_b32_e64 v160, v195, 0, s[4:5]
	v_mov_b32_e32 v193, v173
	v_mov_b32_e32 v199, v173
	v_pk_mul_f32 v[150:151], v[112:113], v[108:109]
	v_mov_b32_dpp v193, v148 row_ror:15 row_mask:0xf bank_mask:0xf
	v_mov_b32_dpp v199, v149 row_ror:15 row_mask:0xf bank_mask:0xf
	v_pk_mul_f32 v[152:153], v[110:111], v[106:107]
	v_mov_b32_e32 v230, v173
	v_mov_b32_e32 v232, v173
	v_mov_b32_e32 v234, v173
	v_mov_b32_e32 v236, v173
	v_mov_b32_dpp v230, v152 row_ror:15 row_mask:0xf bank_mask:0xf
	v_mov_b32_dpp v232, v153 row_ror:15 row_mask:0xf bank_mask:0xf
	v_mov_b32_dpp v234, v150 row_ror:15 row_mask:0xf bank_mask:0xf
	v_mov_b32_dpp v236, v151 row_ror:15 row_mask:0xf bank_mask:0xf
	v_cndmask_b32_e64 v205, v204, v236, s[6:7]
	v_cndmask_b32_e64 v204, v203, v234, s[6:7]
	v_cndmask_b32_e64 v207, v199, v232, s[6:7]
	v_cndmask_b32_e64 v206, v193, v230, s[6:7]
	v_ashrrev_i32_e32 v193, 31, v192
	v_mov_b32_e32 v213, v173
	v_mov_b32_e32 v231, v173
	v_mov_b32_e32 v233, v173
	v_mov_b32_e32 v235, v173
	v_mov_b32_dpp v213, v152 row_ror:1 row_mask:0xf bank_mask:0xf
	v_mov_b32_dpp v231, v153 row_ror:1 row_mask:0xf bank_mask:0xf
	v_mov_b32_dpp v233, v150 row_ror:1 row_mask:0xf bank_mask:0xf
	v_mov_b32_dpp v235, v151 row_ror:1 row_mask:0xf bank_mask:0xf
	v_pk_mul_f32 v[154:155], v[96:97], v[92:93]
	v_pk_mul_f32 v[156:157], v[94:95], v[90:91]
	v_mov_b32_e32 v238, v173
	v_mov_b32_e32 v240, v173
	v_mov_b32_e32 v242, v173
	v_mov_b32_e32 v244, v173
	v_mov_b32_dpp v238, v156 row_ror:15 row_mask:0xf bank_mask:0xf
	v_mov_b32_dpp v240, v157 row_ror:15 row_mask:0xf bank_mask:0xf
	v_mov_b32_dpp v242, v154 row_ror:15 row_mask:0xf bank_mask:0xf
	v_mov_b32_dpp v244, v155 row_ror:15 row_mask:0xf bank_mask:0xf
	v_mov_b32_e32 v241, v173
	v_mov_b32_e32 v243, v173
	v_mov_b32_e32 v237, v173
	v_mov_b32_dpp v241, v154 row_ror:1 row_mask:0xf bank_mask:0xf
	v_mov_b32_dpp v243, v155 row_ror:1 row_mask:0xf bank_mask:0xf
	v_mov_b32_e32 v239, v173
	v_pk_mul_f32 v[144:145], v[80:81], v[76:77]
	v_mov_b32_e32 v250, v173
	v_mov_b32_e32 v252, v173
	v_mov_b32_dpp v237, v156 row_ror:1 row_mask:0xf bank_mask:0xf
	v_mov_b32_dpp v239, v157 row_ror:1 row_mask:0xf bank_mask:0xf
	v_mov_b32_dpp v250, v144 row_ror:15 row_mask:0xf bank_mask:0xf
	v_mov_b32_dpp v252, v145 row_ror:15 row_mask:0xf bank_mask:0xf
	v_pk_mul_f32 v[146:147], v[78:79], v[74:75]
	v_mov_b32_e32 v246, v173
	v_mov_b32_e32 v248, v173
	v_mov_b32_e32 v245, v173
	v_mov_b32_dpp v246, v146 row_ror:15 row_mask:0xf bank_mask:0xf
	v_mov_b32_dpp v248, v147 row_ror:15 row_mask:0xf bank_mask:0xf
	v_mov_b32_e32 v247, v173
	v_mov_b32_dpp v245, v146 row_ror:1 row_mask:0xf bank_mask:0xf
	s_waitcnt vmcnt(0)
	v_pk_mul_f32 v[158:159], v[140:141], v[158:159]
	v_pk_mul_f32 v[160:161], v[138:139], v[160:161]
	v_pk_fma_f32 v[142:143], v[142:143], v[136:137], v[158:159]
	v_mul_f32_e32 v158, 0xbfb8aa3b, v114
	v_mul_f32_e32 v159, 0xbfb8aa3b, v115
	v_exp_f32_e32 v158, v158
	v_exp_f32_e32 v159, v159
	v_pk_fma_f32 v[148:149], v[148:149], v[134:135], v[160:161]
	v_mul_f32_e32 v160, 0xbfb8aa3b, v116
	v_mul_f32_e32 v161, 0xbfb8aa3b, v117
	v_add_f32_e32 v158, 1.0, v158
	v_add_f32_e32 v159, 1.0, v159
	v_exp_f32_e32 v160, v160
	v_exp_f32_e32 v161, v161
	v_rcp_f32_e32 v158, v158
	v_rcp_f32_e32 v159, v159
	v_pk_fma_f32 v[142:143], v[132:133], v[204:205], v[142:143]
	v_pk_fma_f32 v[148:149], v[130:131], v[206:207], v[148:149]
	v_pk_mul_f32 v[142:143], v[120:121], v[142:143]
	v_pk_mul_f32 v[148:149], v[118:119], v[148:149]
	v_add_f32_e32 v160, 1.0, v160
	v_add_f32_e32 v161, 1.0, v161
	v_cvt_pk_bf16_f32 v148, v148, v149
	v_cvt_pk_bf16_f32 v149, v142, v143
	v_lshlrev_b64 v[142:143], 12, v[192:193]
	v_rcp_f32_e32 v160, v160
	v_rcp_f32_e32 v161, v161
	v_mul_f32_e32 v199, v114, v158
	v_mul_f32_e32 v203, v115, v159
	v_lshl_add_u64 v[158:159], s[66:67], 0, v[142:143]
	v_lshlrev_b64 v[142:143], 1, v[172:173]
	v_lshl_add_u64 v[158:159], v[158:159], 0, v[142:143]
	v_mov_b32_e32 v124, v148
	v_mov_b32_e32 v125, v149
	v_lshlrev_b64 v[158:159], 11, v[192:193]
	v_lshl_add_u64 v[158:159], s[48:49], 0, v[158:159]
	v_mul_f32_e32 v160, v116, v160
	v_mul_f32_e32 v161, v117, v161
	v_cvt_pk_bf16_f32 v148, v199, v203
	v_cvt_pk_bf16_f32 v149, v160, v161
	v_lshl_add_u64 v[158:159], v[158:159], 0, v[142:143]
	v_mov_b32_e32 v120, v148
	v_mov_b32_e32 v121, v149
	v_and_b32_e32 v114, 1, v254
	v_cmp_eq_u32_e32 vcc, 1, v114
	v_mov_b32_e32 v116, -8
	v_mov_b32_e32 v115, 0xffff0000
	v_mov_b32_e32 v117, 0xffff8000
	v_cndmask_b32_e32 v114, v115, v116, vcc
	v_cndmask_b32_e32 v116, v117, v116, vcc
; __device__ __forceinline__ unsigned cvt_pk_bf16(float lo, float hi) { unsigned r; asm volatile("v_cvt_pk_bf16_f32 %0, %1, %2" : "=v"(r) : "v"(lo), "v"(hi)); return r; }
;     __host__ __device__ bool next(int i, Unit& u) const { const long L = (long)i * G + c; if (L >= nwg) return false; u.pm = 0; u.pn = c % nN; return true; }
;     __device__ __forceinline__ void operator()(const f32x4 (&acc)[2][2][4][2], const Unit& u, int wr, int wc, int fr, int fq) const {
;     ...
;                 for (int m = 0; m < 4; ++m) {
;                     const f32x4 z = (f32x4){0.f, 0.f, 0.f, 0.f};
;                     const f32x4 prev = fr > 0 ? rr[m] : (m > 0 ? rr[m > 0 ? m - 1 : 0] : z), next = fr < 15 ? ll[m] : (m < 3 ? ll[m < 3 ? m + 1 : 3] : z);
;                     const f32x4 o = acc[ai][1][m][0] * (w0 * prev + w1 * cv[m] + w2 * next);
;                     const f32x4 gq = acc[ai][1][m][1]; f32x4 gs;
; #pragma unroll
;                     for (int e = 0; e < 4; ++e) gs[e] = gq[e] * __builtin_amdgcn_rcpf(1.f + __expf(-gq[e]));
;                     const size_t r = (size_t)(row0 + ai * HALF + m * 16);
;                     *(u32x2*)(CATc + r * ldcat + ch0) = (u32x2){cvt_pk_bf16(o[0], o[1]), cvt_pk_bf16(o[2], o[3])};
;                     *(u32x2*)(GS + r * ldg + ch0) = (u32x2){cvt_pk_bf16(gs[0], gs[1]), cvt_pk_bf16(gs[2], gs[3])};
;                 }
	v_mov_b32_e32 v115, -1
	v_mov_b32_e32 v117, -1
	v_cndmask_b32_e64 v149, v235, v212, s[4:5]
	v_cndmask_b32_e64 v148, v233, v201, s[4:5]
	v_cndmask_b32_e64 v159, v231, v197, s[4:5]
	v_cndmask_b32_e64 v158, v213, v195, s[4:5]
	v_pk_mul_f32 v[148:149], v[140:141], v[148:149]
	v_pk_mul_f32 v[158:159], v[138:139], v[158:159]
	v_pk_fma_f32 v[148:149], v[150:151], v[136:137], v[148:149]
	v_pk_fma_f32 v[150:151], v[152:153], v[134:135], v[158:159]
	v_mul_f32_e32 v152, 0xbfb8aa3b, v98
	v_mul_f32_e32 v153, 0xbfb8aa3b, v99
	v_mul_f32_e32 v158, 0xbfb8aa3b, v100
	v_mul_f32_e32 v159, 0xbfb8aa3b, v101
	v_exp_f32_e32 v152, v152
	v_exp_f32_e32 v153, v153
	v_exp_f32_e32 v158, v158
	v_exp_f32_e32 v159, v159
	v_cndmask_b32_e64 v161, v236, v244, s[6:7]
	v_cndmask_b32_e64 v160, v234, v242, s[6:7]
	v_cndmask_b32_e64 v205, v232, v240, s[6:7]
	v_cndmask_b32_e64 v204, v230, v238, s[6:7]
	v_pk_fma_f32 v[148:149], v[132:133], v[160:161], v[148:149]
	v_pk_fma_f32 v[150:151], v[130:131], v[204:205], v[150:151]
	v_pk_mul_f32 v[148:149], v[104:105], v[148:149]
	v_pk_mul_f32 v[150:151], v[102:103], v[150:151]
	v_ashrrev_i32_e32 v203, 31, v202
	v_add_f32_e32 v152, 1.0, v152
	v_add_f32_e32 v153, 1.0, v153
	v_add_f32_e32 v158, 1.0, v158
	v_add_f32_e32 v159, 1.0, v159
	v_cvt_pk_bf16_f32 v150, v150, v151
	v_cvt_pk_bf16_f32 v151, v148, v149
	v_lshlrev_b64 v[148:149], 12, v[202:203]
	v_rcp_f32_e32 v152, v152
	v_rcp_f32_e32 v153, v153
	v_rcp_f32_e32 v158, v158
	v_rcp_f32_e32 v159, v159
	v_lshl_add_u64 v[148:149], s[66:67], 0, v[148:149]
	v_lshl_add_u64 v[148:149], v[148:149], 0, v[142:143]
	v_mov_b32_e32 v126, v150
	v_mov_b32_e32 v127, v151
	s_nop 1
	v_permlane16_swap_b32 v124, v126
	v_permlane16_swap_b32 v125, v127
	v_lshl_add_u64 v[148:149], v[148:149], 0, v[114:115]
	global_store_dwordx4 v[148:149], v[124:127], off
	v_lshlrev_b64 v[150:151], 11, v[202:203]
	v_lshl_add_u64 v[150:151], s[48:49], 0, v[150:151]
	v_mul_f32_e32 v152, v98, v152
	v_mul_f32_e32 v153, v99, v153
	v_mul_f32_e32 v158, v100, v158
	v_mul_f32_e32 v159, v101, v159
	v_cvt_pk_bf16_f32 v148, v152, v153
	v_cvt_pk_bf16_f32 v149, v158, v159
	v_lshl_add_u64 v[150:151], v[150:151], 0, v[142:143]
	v_mov_b32_e32 v122, v148
	v_mov_b32_e32 v123, v149
	s_nop 1
	v_permlane16_swap_b32 v120, v122
	v_permlane16_swap_b32 v121, v123
	v_lshl_add_u64 v[150:151], v[150:151], 0, v[116:117]
	global_store_dwordx4 v[150:151], v[120:123], off
	v_cndmask_b32_e64 v149, v243, v235, s[4:5]
	v_cndmask_b32_e64 v148, v241, v233, s[4:5]
	v_pk_mul_f32 v[148:149], v[140:141], v[148:149]
	v_cndmask_b32_e64 v151, v239, v231, s[4:5]
	v_cndmask_b32_e64 v150, v237, v213, s[4:5]
	v_cndmask_b32_e64 v153, v244, v252, s[6:7]
	v_cndmask_b32_e64 v152, v242, v250, s[6:7]
	v_pk_fma_f32 v[148:149], v[154:155], v[136:137], v[148:149]
	v_pk_mul_f32 v[150:151], v[138:139], v[150:151]
	v_pk_fma_f32 v[148:149], v[132:133], v[152:153], v[148:149]
	v_mul_f32_e32 v152, 0xbfb8aa3b, v82
	v_mul_f32_e32 v153, 0xbfb8aa3b, v83
	v_mul_f32_e32 v154, 0xbfb8aa3b, v84
	v_mul_f32_e32 v155, 0xbfb8aa3b, v85
	v_cndmask_b32_e64 v159, v240, v248, s[6:7]
	v_cndmask_b32_e64 v158, v238, v246, s[6:7]
	v_pk_fma_f32 v[150:151], v[156:157], v[134:135], v[150:151]
	v_exp_f32_e32 v152, v152
	v_exp_f32_e32 v153, v153
	v_exp_f32_e32 v154, v154
	v_exp_f32_e32 v155, v155
	v_pk_fma_f32 v[150:151], v[130:131], v[158:159], v[150:151]
	v_pk_mul_f32 v[148:149], v[88:89], v[148:149]
	v_pk_mul_f32 v[150:151], v[86:87], v[150:151]
	v_ashrrev_i32_e32 v201, 31, v200
	v_cvt_pk_bf16_f32 v150, v150, v151
	v_cvt_pk_bf16_f32 v151, v148, v149
	v_lshlrev_b64 v[148:149], 12, v[200:201]
	v_add_f32_e32 v152, 1.0, v152
	v_add_f32_e32 v153, 1.0, v153
	v_add_f32_e32 v154, 1.0, v154
	v_add_f32_e32 v155, 1.0, v155
	v_lshl_add_u64 v[148:149], s[66:67], 0, v[148:149]
	v_rcp_f32_e32 v152, v152
	v_rcp_f32_e32 v153, v153
	v_rcp_f32_e32 v154, v154
	v_rcp_f32_e32 v155, v155
	v_lshl_add_u64 v[148:149], v[148:149], 0, v[142:143]
	v_mov_b32_e32 v124, v150
	v_mov_b32_e32 v125, v151
	v_lshlrev_b64 v[150:151], 11, v[200:201]
	v_lshl_add_u64 v[150:151], s[48:49], 0, v[150:151]
	v_mov_b32_dpp v247, v147 row_ror:1 row_mask:0xf bank_mask:0xf
	v_mov_b32_e32 v249, v173
	v_mov_b32_e32 v251, v173
	v_lshl_add_u64 v[150:151], v[150:151], 0, v[142:143]
	v_mov_b32_dpp v249, v144 row_ror:1 row_mask:0xf bank_mask:0xf
	v_mov_b32_dpp v251, v145 row_ror:1 row_mask:0xf bank_mask:0xf
	v_mul_f32_e32 v152, v82, v152
	v_mul_f32_e32 v153, v83, v153
	v_mul_f32_e32 v154, v84, v154
	v_mul_f32_e32 v155, v85, v155
	v_cvt_pk_bf16_f32 v148, v152, v153
	v_cvt_pk_bf16_f32 v149, v154, v155
	v_mov_b32_e32 v120, v148
	v_mov_b32_e32 v121, v149
	v_cndmask_b32_e64 v151, v247, v239, s[4:5]
	v_cndmask_b32_e64 v150, v245, v237, s[4:5]
	v_cndmask_b32_e64 v149, v251, v243, s[4:5]
	v_cndmask_b32_e64 v148, v249, v241, s[4:5]
	v_pk_mul_f32 v[150:151], v[138:139], v[150:151]
	v_pk_mul_f32 v[148:149], v[140:141], v[148:149]
	v_pk_fma_f32 v[146:147], v[146:147], v[134:135], v[150:151]
	v_mul_f32_e32 v150, 0xbfb8aa3b, v68
	v_mul_f32_e32 v151, 0xbfb8aa3b, v69
	v_pk_fma_f32 v[144:145], v[144:145], v[136:137], v[148:149]
	v_mul_f32_e32 v148, 0xbfb8aa3b, v66
	v_mul_f32_e32 v149, 0xbfb8aa3b, v67
	v_exp_f32_e32 v150, v150
	v_exp_f32_e32 v151, v151
	v_exp_f32_e32 v148, v148
	v_exp_f32_e32 v149, v149
	v_cndmask_b32_e64 v153, v252, 0, s[6:7]
	v_cndmask_b32_e64 v152, v250, 0, s[6:7]
	v_cndmask_b32_e64 v155, v248, 0, s[6:7]
	v_cndmask_b32_e64 v154, v246, 0, s[6:7]
	v_add_f32_e32 v150, 1.0, v150
	v_add_f32_e32 v151, 1.0, v151
	v_pk_fma_f32 v[144:145], v[132:133], v[152:153], v[144:145]
	v_pk_fma_f32 v[146:147], v[130:131], v[154:155], v[146:147]
	v_add_f32_e32 v148, 1.0, v148
; __device__ __forceinline__ unsigned cvt_pk_bf16(float lo, float hi) { unsigned r; asm volatile("v_cvt_pk_bf16_f32 %0, %1, %2" : "=v"(r) : "v"(lo), "v"(hi)); return r; }
;     __host__ __device__ bool next(int i, Unit& u) const { const long L = (long)i * G + c; if (L >= nwg) return false; u.pm = 0; u.pn = c % nN; return true; }
;     __device__ __forceinline__ void operator()(const f32x4 (&acc)[2][2][4][2], const Unit& u, int wr, int wc, int fr, int fq) const {
;     ...
;                 for (int m = 0; m < 4; ++m) {
;                     const f32x4 z = (f32x4){0.f, 0.f, 0.f, 0.f};
;                     const f32x4 prev = fr > 0 ? rr[m] : (m > 0 ? rr[m > 0 ? m - 1 : 0] : z), next = fr < 15 ? ll[m] : (m < 3 ? ll[m < 3 ? m + 1 : 3] : z);
;                     const f32x4 o = acc[ai][1][m][0] * (w0 * prev + w1 * cv[m] + w2 * next);
;                     const f32x4 gq = acc[ai][1][m][1]; f32x4 gs;
; #pragma unroll
;                     for (int e = 0; e < 4; ++e) gs[e] = gq[e] * __builtin_amdgcn_rcpf(1.f + __expf(-gq[e]));
;                     const size_t r = (size_t)(row0 + ai * HALF + m * 16);
;                     *(u32x2*)(CATc + r * ldcat + ch0) = (u32x2){cvt_pk_bf16(o[0], o[1]), cvt_pk_bf16(o[2], o[3])};
;                     *(u32x2*)(GS + r * ldg + ch0) = (u32x2){cvt_pk_bf16(gs[0], gs[1]), cvt_pk_bf16(gs[2], gs[3])};
;                 }
	v_add_f32_e32 v149, 1.0, v149
	v_rcp_f32_e32 v150, v150
	v_rcp_f32_e32 v151, v151
	v_rcp_f32_e32 v148, v148
	v_rcp_f32_e32 v149, v149
	v_pk_mul_f32 v[144:145], v[72:73], v[144:145]
	v_pk_mul_f32 v[146:147], v[70:71], v[146:147]
	v_ashrrev_i32_e32 v199, 31, v198
	v_cvt_pk_bf16_f32 v146, v146, v147
	v_cvt_pk_bf16_f32 v147, v144, v145
	v_lshlrev_b64 v[144:145], 12, v[198:199]
	v_lshl_add_u64 v[144:145], s[66:67], 0, v[144:145]
	v_mul_f32_e32 v150, v68, v150
	v_mul_f32_e32 v151, v69, v151
	v_lshl_add_u64 v[144:145], v[144:145], 0, v[142:143]
	v_mul_f32_e32 v148, v66, v148
	v_mul_f32_e32 v149, v67, v149
	v_mov_b32_e32 v126, v146
	v_mov_b32_e32 v127, v147
	s_nop 1
	v_permlane16_swap_b32 v124, v126
	v_permlane16_swap_b32 v125, v127
	v_lshl_add_u64 v[144:145], v[144:145], 0, v[114:115]
	global_store_dwordx4 v[144:145], v[124:127], off
	v_cvt_pk_bf16_f32 v144, v148, v149
	v_cvt_pk_bf16_f32 v145, v150, v151
	v_pk_mul_f32 v[150:151], v[62:63], v[58:59]
	v_mov_b32_e32 v197, v173
	v_pk_mul_f32 v[154:155], v[46:47], v[42:43]
	v_mov_b32_e32 v233, v173
	v_mov_b32_dpp v197, v151 row_ror:15 row_mask:0xf bank_mask:0xf
	v_lshlrev_b64 v[146:147], 11, v[198:199]
	v_mov_b32_dpp v233, v155 row_ror:15 row_mask:0xf bank_mask:0xf
	v_cndmask_b32_e64 v213, v197, v233, s[6:7]
	v_mul_f32_e32 v197, 0xbfb8aa3b, v53
	v_exp_f32_e32 v197, v197
	v_pk_mul_f32 v[148:149], v[64:65], v[60:61]
	v_mov_b32_e32 v199, v173
	v_mov_b32_e32 v203, v173
	v_mov_b32_e32 v172, v173
	v_mov_b32_dpp v199, v148 row_ror:1 row_mask:0xf bank_mask:0xf
	v_mov_b32_dpp v203, v149 row_ror:1 row_mask:0xf bank_mask:0xf
	v_mov_b32_e32 v193, v173
	v_mov_b32_e32 v195, v173
	v_mov_b32_e32 v231, v173
	v_cndmask_b32_e64 v161, v203, 0, s[4:5]
	v_cndmask_b32_e64 v160, v199, 0, s[4:5]
	v_mov_b32_dpp v172, v150 row_ror:1 row_mask:0xf bank_mask:0xf
	v_mov_b32_dpp v193, v150 row_ror:15 row_mask:0xf bank_mask:0xf
	v_mov_b32_dpp v195, v151 row_ror:1 row_mask:0xf bank_mask:0xf
	v_mov_b32_e32 v201, v173
	v_mov_b32_e32 v206, v173
	v_mov_b32_dpp v231, v154 row_ror:15 row_mask:0xf bank_mask:0xf
	v_pk_mul_f32 v[160:161], v[140:141], v[160:161]
	v_add_f32_e32 v197, 1.0, v197
	v_mov_b32_dpp v201, v148 row_ror:15 row_mask:0xf bank_mask:0xf
	v_mov_b32_dpp v206, v149 row_ror:15 row_mask:0xf bank_mask:0xf
	v_pk_mul_f32 v[152:153], v[48:49], v[44:45]
	v_mov_b32_e32 v235, v173
	v_mov_b32_e32 v237, v173
	v_cndmask_b32_e64 v205, v195, 0, s[4:5]
	v_cndmask_b32_e64 v204, v172, 0, s[4:5]
	v_cndmask_b32_e64 v212, v193, v231, s[6:7]
	v_pk_fma_f32 v[148:149], v[148:149], v[136:137], v[160:161]
	v_mul_f32_e32 v160, 0xbfb8aa3b, v50
	v_mul_f32_e32 v161, 0xbfb8aa3b, v51
	v_mul_f32_e32 v193, 0xbfb8aa3b, v52
	v_rcp_f32_e32 v197, v197
	v_mov_b32_dpp v235, v152 row_ror:15 row_mask:0xf bank_mask:0xf
	v_mov_b32_dpp v237, v153 row_ror:15 row_mask:0xf bank_mask:0xf
	v_pk_mul_f32 v[204:205], v[138:139], v[204:205]
	v_exp_f32_e32 v160, v160
	v_exp_f32_e32 v161, v161
	v_exp_f32_e32 v193, v193
	v_cndmask_b32_e64 v207, v206, v237, s[6:7]
	v_cndmask_b32_e64 v206, v201, v235, s[6:7]
	v_pk_fma_f32 v[150:151], v[150:151], v[134:135], v[204:205]
	v_lshl_add_u64 v[146:147], s[48:49], 0, v[146:147]
	v_pk_fma_f32 v[148:149], v[132:133], v[206:207], v[148:149]
	v_pk_fma_f32 v[150:151], v[130:131], v[212:213], v[150:151]
	v_lshl_add_u64 v[146:147], v[146:147], 0, v[142:143]
	v_mul_f32_e32 v201, v53, v197
	v_pk_mul_f32 v[148:149], v[56:57], v[148:149]
	v_pk_mul_f32 v[150:151], v[54:55], v[150:151]
	v_ashrrev_i32_e32 v197, 31, v196
	v_mov_b32_e32 v122, v144
	v_mov_b32_e32 v123, v145
	s_nop 1
	v_permlane16_swap_b32 v120, v122
	v_permlane16_swap_b32 v121, v123
	v_lshl_add_u64 v[146:147], v[146:147], 0, v[116:117]
	global_store_dwordx4 v[146:147], v[120:123], off
	v_add_f32_e32 v160, 1.0, v160
	v_add_f32_e32 v161, 1.0, v161
	v_add_f32_e32 v193, 1.0, v193
	v_cvt_pk_bf16_f32 v150, v150, v151
	v_cvt_pk_bf16_f32 v151, v148, v149
	v_lshlrev_b64 v[148:149], 12, v[196:197]
	v_rcp_f32_e32 v160, v160
	v_rcp_f32_e32 v161, v161
	v_rcp_f32_e32 v193, v193
	v_lshl_add_u64 v[148:149], s[66:67], 0, v[148:149]
	v_lshl_add_u64 v[148:149], v[148:149], 0, v[142:143]
	v_mov_b32_e32 v124, v150
	v_mov_b32_e32 v125, v151
	v_lshlrev_b64 v[150:151], 11, v[196:197]
	v_mov_b32_e32 v230, v173
	v_mov_b32_e32 v232, v173
	v_mov_b32_e32 v234, v173
	v_mov_b32_e32 v236, v173
	v_lshl_add_u64 v[150:151], s[48:49], 0, v[150:151]
	v_mov_b32_dpp v230, v154 row_ror:1 row_mask:0xf bank_mask:0xf
	v_mov_b32_dpp v232, v155 row_ror:1 row_mask:0xf bank_mask:0xf
	v_mov_b32_dpp v234, v152 row_ror:1 row_mask:0xf bank_mask:0xf
	v_mov_b32_dpp v236, v153 row_ror:1 row_mask:0xf bank_mask:0xf
	v_mul_f32_e32 v160, v50, v160
	v_mul_f32_e32 v161, v51, v161
	v_mul_f32_e32 v193, v52, v193
	v_cvt_pk_bf16_f32 v148, v160, v161
	v_cvt_pk_bf16_f32 v149, v193, v201
	v_lshl_add_u64 v[150:151], v[150:151], 0, v[142:143]
	v_mov_b32_e32 v120, v148
	v_mov_b32_e32 v121, v149
	v_cndmask_b32_e64 v149, v236, v203, s[4:5]
	v_cndmask_b32_e64 v148, v234, v199, s[4:5]
	v_cndmask_b32_e64 v151, v232, v195, s[4:5]
	v_cndmask_b32_e64 v150, v230, v172, s[4:5]
	v_pk_mul_f32 v[148:149], v[140:141], v[148:149]
	v_pk_mul_f32 v[150:151], v[138:139], v[150:151]
	v_pk_mul_f32 v[156:157], v[32:33], v[28:29]
	v_pk_mul_f32 v[158:159], v[30:31], v[26:27]
	v_mov_b32_e32 v239, v173
	v_mov_b32_e32 v241, v173
	v_mov_b32_e32 v243, v173
	v_mov_b32_e32 v245, v173
	v_pk_fma_f32 v[148:149], v[152:153], v[136:137], v[148:149]
	v_pk_fma_f32 v[150:151], v[154:155], v[134:135], v[150:151]
	v_mul_f32_e32 v152, 0xbfb8aa3b, v34
	v_mul_f32_e32 v153, 0xbfb8aa3b, v35
	v_mul_f32_e32 v154, 0xbfb8aa3b, v36
	v_mul_f32_e32 v155, 0xbfb8aa3b, v37
	v_mov_b32_dpp v239, v158 row_ror:15 row_mask:0xf bank_mask:0xf
; __device__ __forceinline__ unsigned cvt_pk_bf16(float lo, float hi) { unsigned r; asm volatile("v_cvt_pk_bf16_f32 %0, %1, %2" : "=v"(r) : "v"(lo), "v"(hi)); return r; }
;     __host__ __device__ bool next(int i, Unit& u) const { const long L = (long)i * G + c; if (L >= nwg) return false; u.pm = 0; u.pn = c % nN; return true; }
;     __device__ __forceinline__ void operator()(const f32x4 (&acc)[2][2][4][2], const Unit& u, int wr, int wc, int fr, int fq) const {
;     ...
;                 for (int m = 0; m < 4; ++m) {
;                     const f32x4 z = (f32x4){0.f, 0.f, 0.f, 0.f};
;                     const f32x4 prev = fr > 0 ? rr[m] : (m > 0 ? rr[m > 0 ? m - 1 : 0] : z), next = fr < 15 ? ll[m] : (m < 3 ? ll[m < 3 ? m + 1 : 3] : z);
;                     const f32x4 o = acc[ai][1][m][0] * (w0 * prev + w1 * cv[m] + w2 * next);
;                     const f32x4 gq = acc[ai][1][m][1]; f32x4 gs;
; #pragma unroll
;                     for (int e = 0; e < 4; ++e) gs[e] = gq[e] * __builtin_amdgcn_rcpf(1.f + __expf(-gq[e]));
;                     const size_t r = (size_t)(row0 + ai * HALF + m * 16);
;                     *(u32x2*)(CATc + r * ldcat + ch0) = (u32x2){cvt_pk_bf16(o[0], o[1]), cvt_pk_bf16(o[2], o[3])};
;                     *(u32x2*)(GS + r * ldg + ch0) = (u32x2){cvt_pk_bf16(gs[0], gs[1]), cvt_pk_bf16(gs[2], gs[3])};
;                 }
	v_mov_b32_dpp v241, v159 row_ror:15 row_mask:0xf bank_mask:0xf
	v_mov_b32_dpp v243, v156 row_ror:15 row_mask:0xf bank_mask:0xf
	v_mov_b32_dpp v245, v157 row_ror:15 row_mask:0xf bank_mask:0xf
	v_exp_f32_e32 v152, v152
	v_exp_f32_e32 v153, v153
	v_exp_f32_e32 v154, v154
	v_exp_f32_e32 v155, v155
	v_cndmask_b32_e64 v161, v237, v245, s[6:7]
	v_cndmask_b32_e64 v160, v235, v243, s[6:7]
	v_cndmask_b32_e64 v205, v233, v241, s[6:7]
	v_cndmask_b32_e64 v204, v231, v239, s[6:7]
	v_pk_fma_f32 v[148:149], v[132:133], v[160:161], v[148:149]
	v_pk_fma_f32 v[150:151], v[130:131], v[204:205], v[150:151]
	v_pk_mul_f32 v[148:149], v[40:41], v[148:149]
	v_pk_mul_f32 v[150:151], v[38:39], v[150:151]
	v_ashrrev_i32_e32 v195, 31, v194
	v_add_f32_e32 v152, 1.0, v152
	v_add_f32_e32 v153, 1.0, v153
	v_add_f32_e32 v154, 1.0, v154
	v_add_f32_e32 v155, 1.0, v155
	v_cvt_pk_bf16_f32 v150, v150, v151
	v_cvt_pk_bf16_f32 v151, v148, v149
	v_lshlrev_b64 v[148:149], 12, v[194:195]
	v_rcp_f32_e32 v152, v152
	v_rcp_f32_e32 v153, v153
	v_rcp_f32_e32 v154, v154
	v_rcp_f32_e32 v155, v155
	v_lshl_add_u64 v[148:149], s[66:67], 0, v[148:149]
	v_lshl_add_u64 v[148:149], v[148:149], 0, v[142:143]
	v_mov_b32_e32 v126, v150
	v_mov_b32_e32 v127, v151
	s_nop 1
	v_permlane16_swap_b32 v124, v126
	v_permlane16_swap_b32 v125, v127
	v_lshl_add_u64 v[148:149], v[148:149], 0, v[114:115]
	global_store_dwordx4 v[148:149], v[124:127], off
	v_lshlrev_b64 v[150:151], 11, v[194:195]
	v_mov_b32_e32 v242, v173
	v_mov_b32_e32 v244, v173
	v_lshl_add_u64 v[150:151], s[48:49], 0, v[150:151]
	v_mov_b32_dpp v242, v156 row_ror:1 row_mask:0xf bank_mask:0xf
	v_mov_b32_dpp v244, v157 row_ror:1 row_mask:0xf bank_mask:0xf
	v_mul_f32_e32 v152, v34, v152
	v_mul_f32_e32 v153, v35, v153
	v_mul_f32_e32 v154, v36, v154
	v_mul_f32_e32 v155, v37, v155
	v_cvt_pk_bf16_f32 v148, v152, v153
	v_cvt_pk_bf16_f32 v149, v154, v155
	v_lshl_add_u64 v[150:151], v[150:151], 0, v[142:143]
	v_pk_mul_f32 v[144:145], v[16:17], v[12:13]
	v_mov_b32_e32 v251, v173
	v_mov_b32_e32 v253, v173
	v_mov_b32_e32 v122, v148
	v_mov_b32_e32 v123, v149
	s_nop 1
	v_permlane16_swap_b32 v120, v122
	v_permlane16_swap_b32 v121, v123
	v_lshl_add_u64 v[150:151], v[150:151], 0, v[116:117]
	global_store_dwordx4 v[150:151], v[120:123], off
	v_cndmask_b32_e64 v149, v244, v236, s[4:5]
	v_cndmask_b32_e64 v148, v242, v234, s[4:5]
	v_mov_b32_dpp v251, v144 row_ror:15 row_mask:0xf bank_mask:0xf
	v_mov_b32_dpp v253, v145 row_ror:15 row_mask:0xf bank_mask:0xf
	v_pk_mul_f32 v[148:149], v[140:141], v[148:149]
	v_cndmask_b32_e64 v153, v245, v253, s[6:7]
	v_cndmask_b32_e64 v152, v243, v251, s[6:7]
	v_pk_fma_f32 v[148:149], v[156:157], v[136:137], v[148:149]
	v_mov_b32_e32 v238, v173
	v_pk_fma_f32 v[148:149], v[132:133], v[152:153], v[148:149]
	v_mul_f32_e32 v152, 0xbfb8aa3b, v18
	v_exp_f32_e32 v152, v152
	v_mul_f32_e32 v153, 0xbfb8aa3b, v19
	v_mov_b32_e32 v240, v173
	v_exp_f32_e32 v153, v153
	v_mov_b32_dpp v238, v158 row_ror:1 row_mask:0xf bank_mask:0xf
	v_mov_b32_dpp v240, v159 row_ror:1 row_mask:0xf bank_mask:0xf
	v_pk_mul_f32 v[146:147], v[14:15], v[10:11]
	v_mov_b32_e32 v247, v173
	v_mov_b32_e32 v249, v173
	v_cndmask_b32_e64 v151, v240, v232, s[4:5]
	v_cndmask_b32_e64 v150, v238, v230, s[4:5]
	v_mov_b32_dpp v247, v146 row_ror:15 row_mask:0xf bank_mask:0xf
	v_mov_b32_dpp v249, v147 row_ror:15 row_mask:0xf bank_mask:0xf
	v_pk_mul_f32 v[150:151], v[138:139], v[150:151]
	v_add_f32_e32 v152, 1.0, v152
	v_cndmask_b32_e64 v155, v241, v249, s[6:7]
	v_cndmask_b32_e64 v154, v239, v247, s[6:7]
	v_pk_fma_f32 v[150:151], v[158:159], v[134:135], v[150:151]
	v_rcp_f32_e32 v152, v152
	v_add_f32_e32 v153, 1.0, v153
	v_pk_fma_f32 v[150:151], v[130:131], v[154:155], v[150:151]
	v_mul_f32_e32 v154, 0xbfb8aa3b, v20
	v_mul_f32_e32 v155, 0xbfb8aa3b, v21
; __device__ __forceinline__ unsigned cvt_pk_bf16(float lo, float hi) { unsigned r; asm volatile("v_cvt_pk_bf16_f32 %0, %1, %2" : "=v"(r) : "v"(lo), "v"(hi)); return r; }
;     __host__ __device__ bool next(int i, Unit& u) const { const long L = (long)i * G + c; if (L >= nwg) return false; u.pm = 0; u.pn = c % nN; return true; }
;     __device__ __forceinline__ void operator()(const f32x4 (&acc)[2][2][4][2], const Unit& u, int wr, int wc, int fr, int fq) const {
;     ...
;                 for (int m = 0; m < 4; ++m) {
;                     const f32x4 z = (f32x4){0.f, 0.f, 0.f, 0.f};
;                     const f32x4 prev = fr > 0 ? rr[m] : (m > 0 ? rr[m > 0 ? m - 1 : 0] : z), next = fr < 15 ? ll[m] : (m < 3 ? ll[m < 3 ? m + 1 : 3] : z);
;                     const f32x4 o = acc[ai][1][m][0] * (w0 * prev + w1 * cv[m] + w2 * next);
;                     const f32x4 gq = acc[ai][1][m][1]; f32x4 gs;
; #pragma unroll
;                     for (int e = 0; e < 4; ++e) gs[e] = gq[e] * __builtin_amdgcn_rcpf(1.f + __expf(-gq[e]));
;                     const size_t r = (size_t)(row0 + ai * HALF + m * 16);
;                     *(u32x2*)(CATc + r * ldcat + ch0) = (u32x2){cvt_pk_bf16(o[0], o[1]), cvt_pk_bf16(o[2], o[3])};
;                     *(u32x2*)(GS + r * ldg + ch0) = (u32x2){cvt_pk_bf16(gs[0], gs[1]), cvt_pk_bf16(gs[2], gs[3])};
;                 }
	v_rcp_f32_e32 v153, v153
	v_exp_f32_e32 v154, v154
	v_exp_f32_e32 v155, v155
	v_mul_f32_e32 v156, v18, v152
	v_add_u32_e32 v152, 0xa0, v192
	v_mul_f32_e32 v157, v19, v153
	v_pk_mul_f32 v[148:149], v[24:25], v[148:149]
	v_pk_mul_f32 v[150:151], v[22:23], v[150:151]
	v_ashrrev_i32_e32 v153, 31, v152
	v_add_f32_e32 v154, 1.0, v154
	v_add_f32_e32 v155, 1.0, v155
	v_cvt_pk_bf16_f32 v150, v150, v151
	v_cvt_pk_bf16_f32 v151, v148, v149
	v_lshlrev_b64 v[148:149], 12, v[152:153]
	v_rcp_f32_e32 v154, v154
	v_rcp_f32_e32 v155, v155
	v_lshl_add_u64 v[148:149], s[66:67], 0, v[148:149]
	v_lshl_add_u64 v[148:149], v[148:149], 0, v[142:143]
	v_mov_b32_e32 v124, v150
	v_mov_b32_e32 v125, v151
	v_lshlrev_b64 v[150:151], 11, v[152:153]
	v_mov_b32_e32 v250, v173
	v_mov_b32_e32 v252, v173
	v_lshl_add_u64 v[150:151], s[48:49], 0, v[150:151]
	v_mov_b32_dpp v250, v144 row_ror:1 row_mask:0xf bank_mask:0xf
	v_mov_b32_dpp v252, v145 row_ror:1 row_mask:0xf bank_mask:0xf
	v_mul_f32_e32 v154, v20, v154
	v_mul_f32_e32 v155, v21, v155
	v_cvt_pk_bf16_f32 v148, v156, v157
	v_cvt_pk_bf16_f32 v149, v154, v155
	v_lshl_add_u64 v[150:151], v[150:151], 0, v[142:143]
	v_mov_b32_e32 v120, v148
	v_mov_b32_e32 v121, v149
	v_cndmask_b32_e64 v149, v252, v244, s[4:5]
	v_cndmask_b32_e64 v148, v250, v242, s[4:5]
	v_pk_mul_f32 v[140:141], v[140:141], v[148:149]
	v_cndmask_b32_e64 v153, v253, 0, s[6:7]
	v_cndmask_b32_e64 v152, v251, 0, s[6:7]
	v_pk_fma_f32 v[136:137], v[144:145], v[136:137], v[140:141]
	v_mov_b32_e32 v246, v173
	v_mov_b32_e32 v248, v173
	v_pk_fma_f32 v[132:133], v[132:133], v[152:153], v[136:137]
	v_mul_f32_e32 v136, 0xbfb8aa3b, v2
	v_mov_b32_dpp v246, v146 row_ror:1 row_mask:0xf bank_mask:0xf
	v_mov_b32_dpp v248, v147 row_ror:1 row_mask:0xf bank_mask:0xf
	v_exp_f32_e32 v136, v136
	v_mul_f32_e32 v137, 0xbfb8aa3b, v3
	v_cndmask_b32_e64 v151, v248, v240, s[4:5]
	v_cndmask_b32_e64 v150, v246, v238, s[4:5]
	v_exp_f32_e32 v137, v137
	v_pk_mul_f32 v[138:139], v[138:139], v[150:151]
	v_cndmask_b32_e64 v155, v249, 0, s[6:7]
	v_cndmask_b32_e64 v154, v247, 0, s[6:7]
	v_pk_fma_f32 v[134:135], v[146:147], v[134:135], v[138:139]
	v_pk_mul_f32 v[132:133], v[8:9], v[132:133]
	v_pk_fma_f32 v[130:131], v[130:131], v[154:155], v[134:135]
	v_add_f32_e32 v134, 1.0, v136
	v_rcp_f32_e32 v134, v134
	v_add_f32_e32 v135, 1.0, v137
	v_rcp_f32_e32 v135, v135
	v_mul_f32_e32 v136, 0xbfb8aa3b, v4
	v_mul_f32_e32 v137, 0xbfb8aa3b, v5
	v_exp_f32_e32 v136, v136
	v_exp_f32_e32 v137, v137
	v_mul_f32_e32 v138, v2, v134
	v_add_u32_e32 v134, 0xb0, v192
	v_mul_f32_e32 v139, v3, v135
	v_pk_mul_f32 v[130:131], v[6:7], v[130:131]
	v_ashrrev_i32_e32 v135, 31, v134
	v_cvt_pk_bf16_f32 v130, v130, v131
	v_cvt_pk_bf16_f32 v131, v132, v133
	v_lshlrev_b64 v[132:133], 12, v[134:135]
	v_add_f32_e32 v136, 1.0, v136
	v_add_f32_e32 v137, 1.0, v137
	v_lshl_add_u64 v[132:133], s[66:67], 0, v[132:133]
	v_rcp_f32_e32 v136, v136
	v_rcp_f32_e32 v137, v137
	v_lshl_add_u64 v[132:133], v[132:133], 0, v[142:143]
	v_mov_b32_e32 v126, v130
	v_mov_b32_e32 v127, v131
	s_nop 1
	v_permlane16_swap_b32 v124, v126
	v_permlane16_swap_b32 v125, v127
	v_lshl_add_u64 v[132:133], v[132:133], 0, v[114:115]
	global_store_dwordx4 v[132:133], v[124:127], off
	v_lshlrev_b64 v[132:133], 11, v[134:135]
	v_lshl_add_u64 v[132:133], s[48:49], 0, v[132:133]
	v_lshl_add_u64 v[132:133], v[132:133], 0, v[142:143]
	v_mul_f32_e32 v136, v4, v136
	v_mul_f32_e32 v137, v5, v137
	v_cvt_pk_bf16_f32 v130, v138, v139
	v_cvt_pk_bf16_f32 v131, v136, v137
	v_mov_b32_e32 v122, v130
	v_mov_b32_e32 v123, v131
	s_nop 1
	v_permlane16_swap_b32 v120, v122
	v_permlane16_swap_b32 v121, v123
	v_lshl_add_u64 v[132:133], v[132:133], 0, v[116:117]
	global_store_dwordx4 v[132:133], v[120:123], off
	s_cbranch_execnz .LBB0_260
